# v49 + attn_sample permlane reductions and batched PV reads + ret_out jt-loop V reads hoisted to iteration top
# speedup vs baseline: 1.0095x; 1.0005x over previous
; DEV f32x4 mfma32(bf16x8 a, bf16x8 b, f32x4 c) { return __builtin_amdgcn_mfma_f32_16x16x32_bf16(a, b, c, 0, 0, 0); }
; DEV f32x4 mfma16(bf16x4 a, bf16x4 b, f32x4 c) { return __builtin_amdgcn_mfma_f32_16x16x16bf16_1k(a, b, c, 0, 0, 0); }
; DEV void ret_out_item(const Params& p, int l, int item, unsigned char* smem) {
;     ...
;   for (int jt = 0; jt <= w; ++jt) {
;     f32x4 s = (f32x4){0.f, 0.f, 0.f, 0.f};
; #pragma unroll
;     for (int ks = 0; ks < 2; ++ks) {
;       const bf16x8 kf = *(const bf16x8*)(Ks + (jt * 16 + fr) * 144 + ks * 64 + fq * 16);
;       s = mfma32(kf, qf[ks], s);
;     }
;     float pv[4];
; #pragma unroll
;     for (int jj = 0; jj < 4; ++jj) {
;       const int kj = jt * 16 + fq * 4 + jj;
;       pv[jj] = (qi >= kj) ? s[jj] * 0.125f * __expf(lg * (float)(qi - kj)) : 0.f;
;     }
;     const bf16x4 pf = pack4(pv[0], pv[1], pv[2], pv[3]);
; #pragma unroll
;     for (int et = 0; et < 8; ++et) {
;       const bf16x4 vf = *(const bf16x4*)(Vt + (et * 16 + fr) * 136 + jt * 16 + fq * 4);
;       a1[et] = mfma16(pf, vf, a1[et]);
;     }
;   }
.LBB0_87:
	s_or_b64 exec, exec, s[4:5]
	s_nop 4
	v_cvt_f32_i32_e32 v73, v87
	v_mul_f32_e32 v72, 0x3e000000, v72
	v_cmp_ge_i32_e32 vcc, v82, v88
	v_or_b32_e32 v92, 3, v88
	v_mul_f32_e32 v73, v90, v73
	v_mul_f32_e32 v73, 0x3fb8aa3b, v73
	v_exp_f32_e32 v73, v73
	v_or_b32_e32 v93, 2, v88
	s_mov_b32 s4, 0x3e000000
	v_pk_mul_f32 v[74:75], v[74:75], s[4:5] op_sel_hi:[1,0]
	v_mul_f32_e32 v72, v72, v73
	v_cndmask_b32_e32 v91, 0, v72, vcc
	v_sub_u32_e32 v72, v82, v93
	v_sub_u32_e32 v73, v82, v92
	v_cvt_f32_i32_e32 v72, v72
	v_cvt_f32_i32_e32 v73, v73
	v_cmp_ge_i32_e32 vcc, v82, v93
	s_mov_b32 s4, 0x5040100
	v_mul_f32_e32 v72, v90, v72
	v_mul_f32_e32 v73, v90, v73
	v_mul_f32_e32 v72, 0x3fb8aa3b, v72
	v_mul_f32_e32 v73, 0x3fb8aa3b, v73
	v_exp_f32_e32 v72, v72
	v_exp_f32_e32 v73, v73
	v_add_u32_e32 v84, -1, v84
	v_add_u32_e32 v86, 0x900, v86
	v_add_u32_e32 v88, 16, v88
	v_pk_mul_f32 v[72:73], v[74:75], v[72:73]
	v_cvt_pk_bf16_f32 v74, v91, v89
	v_cvt_pk_bf16_f32 v72, v72, v73
	v_cndmask_b32_e32 v73, 0, v72, vcc
	v_lshrrev_b32_e32 v72, 16, v72
	v_cmp_ge_i32_e32 vcc, v77, v92
	v_add_u32_e32 v85, 32, v85
	s_nop 0
	v_cndmask_b32_e32 v72, 0, v72, vcc
	v_perm_b32 v75, v72, v73, s4
	v_cmp_eq_u32_e32 vcc, 0, v84
	v_add_u32_e32 v87, -16, v87
	s_nop 0
	s_or_b64 s[2:3], vcc, s[2:3]
	s_waitcnt lgkmcnt(7)
	v_mfma_f32_16x16x16_bf16 v[32:35], v[74:75], v[128:129], v[32:35]
	s_waitcnt lgkmcnt(6)
	v_mfma_f32_16x16x16_bf16 v[36:39], v[74:75], v[130:131], v[36:39]
	s_waitcnt lgkmcnt(5)
	v_mfma_f32_16x16x16_bf16 v[56:59], v[74:75], v[132:133], v[56:59]
	s_waitcnt lgkmcnt(4)
	v_mfma_f32_16x16x16_bf16 v[60:63], v[74:75], v[134:135], v[60:63]
	s_waitcnt lgkmcnt(3)
	v_mfma_f32_16x16x16_bf16 v[40:43], v[74:75], v[136:137], v[40:43]
	s_waitcnt lgkmcnt(2)
	v_mfma_f32_16x16x16_bf16 v[48:51], v[74:75], v[138:139], v[48:51]
	s_waitcnt lgkmcnt(1)
	v_mfma_f32_16x16x16_bf16 v[44:47], v[74:75], v[140:141], v[44:47]
	s_waitcnt lgkmcnt(0)
	v_mfma_f32_16x16x16_bf16 v[52:55], v[74:75], v[142:143], v[52:55]
	s_andn2_b64 exec, exec, s[2:3]
	s_cbranch_execz .LBB0_90
.LBB0_88:
	v_add_u32_e32 v89, 0, v86
	ds_read_b128 v[72:75], v89
	ds_read_b128 v[92:95], v89 offset:64
	v_add_u32_e32 v144, 0, v85
	ds_read_b64 v[128:129], v144 offset:36864
	ds_read_b64 v[130:131], v144 offset:41216
	ds_read_b64 v[132:133], v144 offset:45568
	ds_read_b64 v[134:135], v144 offset:49920
	ds_read_b64 v[136:137], v144 offset:54272
	ds_read_b64 v[138:139], v144 offset:58624
	ds_read_b64 v[140:141], v144 offset:62976
	v_add_u32_e32 v145, 0x10700, v144
	ds_read_b64 v[142:143], v145
	v_cmp_gt_i32_e32 vcc, v82, v88
	v_mov_b32_e32 v89, 0
	s_waitcnt lgkmcnt(9)
	v_mfma_f32_16x16x32_bf16 v[72:75], v[72:75], v[64:67], 0
	s_waitcnt lgkmcnt(8)
	v_mfma_f32_16x16x32_bf16 v[72:75], v[92:95], v[68:71], v[72:75]
	s_and_saveexec_b64 s[4:5], vcc
	s_cbranch_execz .LBB0_87
	v_add_u32_e32 v89, -1, v87
	v_cvt_f32_i32_e32 v89, v89
	s_nop 3
	v_mul_f32_e32 v73, 0x3e000000, v73
	v_mul_f32_e32 v89, v90, v89
	v_mul_f32_e32 v89, 0x3fb8aa3b, v89
	v_exp_f32_e32 v89, v89
	s_nop 0
	v_mul_f32_e32 v89, v73, v89
	s_branch .LBB0_87

; DEV f32x4 mfma32(bf16x8 a, bf16x8 b, f32x4 c) { return __builtin_amdgcn_mfma_f32_16x16x32_bf16(a, b, c, 0, 0, 0); }
; DEV void attn_sample_item(const Params& p, int l, int item, unsigned char* smem) {
;     ...
;     if (tid < 256) *(u32x4*)(Qs + (tid >> 3) * 144 + (tid & 7) * 16) = qv;
;   }
;   __syncthreads();
;   {
;     const int qt = w & 1, dt = w >> 1;
;     const int r = qt * 16 + fr, qi = r & 7, hh = kvh * 4 + (r >> 3);
;     bf16x8 qf[2];
; #pragma unroll
;     for (int ks = 0; ks < 2; ++ks) qf[ks] = *(const bf16x8*)(Qs + r * 144 + ks * 64 + fq * 16);
;     f32x4 s[9];
; #pragma unroll
;     for (int t = 0; t < 9; ++t) {
;       s[t] = (f32x4){0.f, 0.f, 0.f, 0.f};
; #pragma unroll
;       for (int ks = 0; ks < 2; ++ks) {
;         const bf16x8 kf = *(const bf16x8*)(Ks + (t * 16 + fr) * 144 + ks * 64 + fq * 16);
;         s[t] = mfma32(kf, qf[ks], s[t]);
;       }
;     }
;     const float slope = exp2f(-(float)(hh + 1));
;     const float sink = p.in[I_SINKS][l * 8 + hh];
;     float mx = sink;
; #pragma unroll
;     for (int t = 0; t < 9; ++t)
; #pragma unroll
;       for (int j = 0; j < 4; ++j) {
;         const int kj = t * 16 + fq * 4 + j;
;         const bool okk = (kj > qi) && (kj <= 128 + qi);
;         const float sc = okk ? s[t][j] * 0.125f - slope * (float)(128 + qi - kj) : -INFINITY;
;         s[t][j] = sc; mx = fmaxf(mx, sc);
;       }
.LBB0_350:
	s_or_b64 exec, exec, s[2:3]
	s_and_saveexec_b64 s[0:1], vcc
	v_add3_u32 v4, 0, v4, v38
	ds_write_b128 v4, v[0:3] offset:40192
	s_or_b64 exec, exec, s[0:1]
	v_lshlrev_b32_e32 v0, 4, v36
	v_and_b32_e32 v38, 15, v47
	v_and_b32_e32 v39, 16, v0
	v_and_b32_e32 v1, 48, v47
	v_or_b32_e32 v0, v39, v38
	v_add_u32_e32 v1, 0, v1
	v_lshrrev_b32_e32 v36, 3, v0
	v_mad_u32_u24 v0, v0, s33, v1
	v_mad_u32_u24 v37, v38, s33, v1
	s_waitcnt lgkmcnt(0)
	s_barrier
	ds_read_b128 v[32:35], v0 offset:40192
	ds_read_b128 v[50:53], v0 offset:40256
	ds_read_b128 v[64:67], v37
	ds_read_b128 v[68:71], v37 offset:64
	ds_read_b128 v[72:75], v37 offset:2304
	ds_read_b128 v[76:79], v37 offset:2368
	ds_read_b128 v[80:83], v37 offset:4608
	ds_read_b128 v[84:87], v37 offset:4672
	ds_read_b128 v[88:91], v37 offset:6912
	ds_read_b128 v[92:95], v37 offset:6976
	ds_read_b128 v[96:99], v37 offset:9216
	ds_read_b128 v[100:103], v37 offset:9280
	ds_read_b128 v[104:107], v37 offset:11520
	ds_read_b128 v[108:111], v37 offset:11584
	ds_read_b128 v[112:115], v37 offset:13824
	ds_read_b128 v[116:119], v37 offset:13888
	ds_read_b128 v[120:123], v37 offset:16128
	ds_read_b128 v[124:127], v37 offset:16192
	ds_read_b128 v[128:131], v37 offset:18432
	ds_read_b128 v[132:135], v37 offset:18496
	s_lshl_b32 s2, s26, 2
	v_or_b32_e32 v36, s2, v36
	v_or_b32_e32 v44, s18, v36
	v_ashrrev_i32_e32 v45, 31, v44
	v_lshl_add_u64 v[44:45], v[44:45], 2, s[82:83]
	global_load_dword v42, v[44:45], off
	v_lshrrev_b32_e32 v40, 4, v49
	v_and_b32_e32 v43, 7, v47
	v_lshlrev_b32_e32 v168, 1, v38
	s_waitcnt lgkmcnt(15)
	v_mfma_f32_16x16x32_bf16 v[28:31], v[64:67], v[32:35], 0
	v_mfma_f32_16x16x32_bf16 v[28:31], v[68:71], v[50:53], v[28:31]
	s_waitcnt lgkmcnt(14)
	v_mfma_f32_16x16x32_bf16 v[24:27], v[72:75], v[32:35], 0
	v_mfma_f32_16x16x32_bf16 v[24:27], v[76:79], v[50:53], v[24:27]
	s_waitcnt lgkmcnt(12)
	v_mfma_f32_16x16x32_bf16 v[20:23], v[80:83], v[32:35], 0
	v_mfma_f32_16x16x32_bf16 v[20:23], v[84:87], v[50:53], v[20:23]
	s_waitcnt lgkmcnt(10)
	v_mfma_f32_16x16x32_bf16 v[16:19], v[88:91], v[32:35], 0
	v_mfma_f32_16x16x32_bf16 v[16:19], v[92:95], v[50:53], v[16:19]
	s_waitcnt lgkmcnt(8)
	v_mfma_f32_16x16x32_bf16 v[12:15], v[96:99], v[32:35], 0
	v_mfma_f32_16x16x32_bf16 v[12:15], v[100:103], v[50:53], v[12:15]
	s_waitcnt lgkmcnt(6)
	v_mfma_f32_16x16x32_bf16 v[8:11], v[104:107], v[32:35], 0
	v_mfma_f32_16x16x32_bf16 v[8:11], v[108:111], v[50:53], v[8:11]
	s_waitcnt lgkmcnt(4)
	v_mfma_f32_16x16x32_bf16 v[4:7], v[112:115], v[32:35], 0
	v_mfma_f32_16x16x32_bf16 v[4:7], v[116:119], v[50:53], v[4:7]
	s_waitcnt lgkmcnt(2)
	v_mfma_f32_16x16x32_bf16 v[0:3], v[120:123], v[32:35], 0
	v_mfma_f32_16x16x32_bf16 v[0:3], v[124:127], v[50:53], v[0:3]
	v_add_u32_e32 v37, 1, v36
	v_cvt_f32_ubyte0_e32 v37, v37
	v_cmp_lt_f32_e32 vcc, s41, v37
	s_waitcnt lgkmcnt(0)
	v_mfma_f32_16x16x32_bf16 v[32:35], v[128:131], v[32:35], 0
	v_mfma_f32_16x16x32_bf16 v[32:35], v[132:135], v[50:53], v[32:35]
	v_cndmask_b32_e32 v41, 0, v203, vcc
	v_sub_f32_e32 v37, v41, v37
	v_exp_f32_e32 v37, v37
	v_cndmask_b32_e32 v41, 0, v207, vcc
	v_or_b32_e32 v51, 0x80, v43
	v_ldexp_f32 v37, v37, v41
	v_lshlrev_b32_e32 v41, 2, v40
	v_sub_u32_e32 v36, v51, v41
	v_cvt_f32_ubyte0_e32 v179, v36
	v_mov_b32_e32 v36, v28
	v_pk_mul_f32 v[44:45], v[36:37], v[178:179]
	v_sub_co_u32_e32 v52, vcc, v43, v41
	v_sub_f32_e32 v28, v44, v45
	s_nop 0
	v_cndmask_b32_e32 v44, v205, v28, vcc
	v_xad_u32 v28, v41, -1, v51
	v_cvt_f32_ubyte0_e32 v179, v28
	v_mov_b32_e32 v36, v29
	v_pk_mul_f32 v[28:29], v[36:37], v[178:179]
	v_cmp_le_u32_e64 s[0:1], v43, v41
	v_sub_f32_e32 v28, v28, v29
	v_mov_b32_e32 v36, v30
	v_cndmask_b32_e64 v45, v205, v28, s[0:1]
	v_or_b32_e32 v28, 2, v41
	v_cmp_gt_u32_e64 s[0:1], v28, v43
	v_sub_u32_e32 v28, v51, v28
	v_cvt_f32_ubyte0_e32 v179, v28
	v_pk_mul_f32 v[28:29], v[36:37], v[178:179]
	v_mov_b32_e32 v36, v31
	v_sub_f32_e32 v28, v28, v29
	v_cndmask_b32_e64 v46, v205, v28, s[0:1]
	v_or_b32_e32 v28, 3, v41
	v_cmp_gt_u32_e64 s[0:1], v28, v43
	v_sub_u32_e32 v28, v51, v28
	v_cvt_f32_ubyte0_e32 v179, v28
	v_pk_mul_f32 v[28:29], v[36:37], v[178:179]
	v_sub_u32_e32 v50, v43, v41
	v_sub_f32_e32 v28, v28, v29
	v_cndmask_b32_e64 v49, v205, v28, s[0:1]
	v_add_u32_e32 v28, 14, v50
	v_cvt_f32_u32_e32 v179, v28
	v_mov_b32_e32 v36, v2
	s_movk_i32 s0, 0x130
	v_pk_mul_f32 v[28:29], v[36:37], v[178:179]
	s_nop 0
	v_sub_f32_e32 v2, v28, v29
	v_add_u32_e32 v28, 13, v50
	v_cvt_f32_u32_e32 v179, v28
	v_mov_b32_e32 v36, v3
	v_pk_mul_f32 v[28:29], v[36:37], v[178:179]
	v_cvt_f32_u32_e32 v179, v52
	v_mov_b32_e32 v36, v32
	v_sub_f32_e32 v3, v28, v29
	v_pk_mul_f32 v[28:29], v[36:37], v[178:179]
	s_nop 0
	v_sub_f32_e32 v28, v28, v29
	v_or_b32_e32 v29, 0x81, v41
	v_cndmask_b32_e32 v28, v28, v205, vcc
	v_sub_co_u32_e32 v29, vcc, v51, v29
	v_cvt_f32_u32_e32 v179, v29
	v_mov_b32_e32 v36, v33
	v_pk_mul_f32 v[30:31], v[36:37], v[178:179]
	s_nop 0
	v_sub_f32_e32 v29, v30, v31
	v_or_b32_e32 v30, 0x82, v41
	v_cndmask_b32_e32 v29, v29, v205, vcc
	v_sub_co_u32_e32 v30, vcc, v51, v30
	v_cvt_f32_u32_e32 v179, v30
	v_mov_b32_e32 v36, v34
	v_pk_mul_f32 v[30:31], v[36:37], v[178:179]
	s_nop 0
	v_sub_f32_e32 v30, v30, v31
	v_or_b32_e32 v31, 0x83, v41
	v_cndmask_b32_e32 v30, v30, v205, vcc
	v_sub_co_u32_e32 v31, vcc, v51, v31
	v_cvt_f32_u32_e32 v179, v31
	v_mov_b32_e32 v36, v35
	v_pk_mul_f32 v[32:33], v[36:37], v[178:179]
	s_nop 0
	v_sub_f32_e32 v31, v32, v33
	s_waitcnt vmcnt(0)
; DEV void attn_sample_item(const Params& p, int l, int item, unsigned char* smem) {
;     ...
; #pragma unroll
;     for (int t = 0; t < 9; ++t)
; #pragma unroll
;       for (int j = 0; j < 4; ++j) {
;         const int kj = t * 16 + fq * 4 + j;
;         const bool okk = (kj > qi) && (kj <= 128 + qi);
;         const float sc = okk ? s[t][j] * 0.125f - slope * (float)(128 + qi - kj) : -INFINITY;
;         s[t][j] = sc; mx = fmaxf(mx, sc);
;       }
;     mx = fmaxf(mx, __shfl_xor(mx, 16)); mx = fmaxf(mx, __shfl_xor(mx, 32));
;     float sum = 0.f;
; #pragma unroll
;     for (int t = 0; t < 9; ++t)
; #pragma unroll
;       for (int j = 0; j < 4; ++j) { const float e = __expf(s[t][j] - mx); s[t][j] = e; sum += e; }
;     sum += __shfl_xor(sum, 16); sum += __shfl_xor(sum, 32);
	v_max3_f32 v32, v42, v44, v45
	v_max3_f32 v34, v32, v46, v49
	v_or_b32_e32 v32, 0x70, v43
	v_sub_u32_e32 v32, v32, v41
	v_cvt_f32_ubyte0_e32 v179, v32
	v_mov_b32_e32 v36, v24
	v_pk_mul_f32 v[32:33], v[36:37], v[178:179]
	v_mov_b32_e32 v36, v25
	v_sub_f32_e32 v24, v32, v33
	v_add_u32_e32 v32, 0x6f, v50
	v_cvt_f32_u32_e32 v179, v32
	v_cndmask_b32_e32 v31, v31, v205, vcc
	v_pk_mul_f32 v[32:33], v[36:37], v[178:179]
	s_nop 0
	v_sub_f32_e32 v25, v32, v33
	v_add_u32_e32 v32, 0x6e, v50
	v_cvt_f32_u32_e32 v179, v32
	v_mov_b32_e32 v36, v26
	v_max3_f32 v34, v34, v24, v25
	v_pk_mul_f32 v[32:33], v[36:37], v[178:179]
	s_nop 0
	v_sub_f32_e32 v26, v32, v33
	v_add_u32_e32 v32, 0x6d, v50
	v_cvt_f32_u32_e32 v179, v32
	v_mov_b32_e32 v36, v27
	v_pk_mul_f32 v[32:33], v[36:37], v[178:179]
	s_nop 0
	v_sub_f32_e32 v27, v32, v33
	v_or_b32_e32 v32, 0x60, v43
	v_sub_u32_e32 v32, v32, v41
	v_cvt_f32_ubyte0_e32 v179, v32
	v_mov_b32_e32 v36, v20
	v_pk_mul_f32 v[32:33], v[36:37], v[178:179]
	v_mov_b32_e32 v36, v21
	v_sub_f32_e32 v20, v32, v33
	v_add_u32_e32 v32, 0x5f, v50
	v_cvt_f32_u32_e32 v179, v32
	v_max3_f32 v34, v34, v26, v27
	v_pk_mul_f32 v[32:33], v[36:37], v[178:179]
	s_nop 0
	v_sub_f32_e32 v21, v32, v33
	v_add_u32_e32 v32, 0x5e, v50
	v_cvt_f32_u32_e32 v179, v32
	v_mov_b32_e32 v36, v22
	v_add_u32_e32 v22, 0x5d, v50
	v_max3_f32 v34, v34, v20, v21
	v_pk_mul_f32 v[32:33], v[36:37], v[178:179]
	v_cvt_f32_u32_e32 v179, v22
	v_mov_b32_e32 v36, v23
	v_sub_f32_e32 v32, v32, v33
	v_pk_mul_f32 v[22:23], v[36:37], v[178:179]
	s_nop 0
	v_sub_f32_e32 v33, v22, v23
	v_or_b32_e32 v22, 0x50, v43
	v_sub_u32_e32 v22, v22, v41
	v_cvt_f32_ubyte0_e32 v179, v22
	v_mov_b32_e32 v36, v16
	v_add_u32_e32 v16, 0x4f, v50
	v_pk_mul_f32 v[22:23], v[36:37], v[178:179]
	v_cvt_f32_u32_e32 v179, v16
	v_mov_b32_e32 v36, v17
	v_sub_f32_e32 v22, v22, v23
	v_max3_f32 v34, v34, v32, v33
	v_pk_mul_f32 v[16:17], v[36:37], v[178:179]
	v_mov_b32_e32 v36, v18
	v_sub_f32_e32 v23, v16, v17
	v_add_u32_e32 v16, 0x4e, v50
	v_cvt_f32_u32_e32 v179, v16
	v_max3_f32 v34, v34, v22, v23
	v_pk_mul_f32 v[16:17], v[36:37], v[178:179]
	s_nop 0
	v_sub_f32_e32 v18, v16, v17
	v_add_u32_e32 v16, 0x4d, v50
	v_cvt_f32_u32_e32 v179, v16
	v_mov_b32_e32 v36, v19
	v_pk_mul_f32 v[16:17], v[36:37], v[178:179]
	s_nop 0
	v_sub_f32_e32 v19, v16, v17
	v_or_b32_e32 v16, 64, v43
	v_sub_u32_e32 v16, v16, v41
	v_cvt_f32_ubyte0_e32 v179, v16
	v_mov_b32_e32 v36, v12
	v_add_u32_e32 v12, 63, v50
	v_pk_mul_f32 v[16:17], v[36:37], v[178:179]
	v_cvt_f32_u32_e32 v179, v12
	v_mov_b32_e32 v36, v13
	v_sub_f32_e32 v16, v16, v17
	v_max3_f32 v34, v34, v18, v19
	v_pk_mul_f32 v[12:13], v[36:37], v[178:179]
	v_mov_b32_e32 v36, v14
	v_sub_f32_e32 v17, v12, v13
	v_add_u32_e32 v12, 62, v50
	v_cvt_f32_u32_e32 v179, v12
	v_max3_f32 v34, v34, v16, v17
	v_pk_mul_f32 v[12:13], v[36:37], v[178:179]
	s_nop 0
	v_sub_f32_e32 v14, v12, v13
	v_add_u32_e32 v12, 61, v50
	v_cvt_f32_u32_e32 v179, v12
	v_mov_b32_e32 v36, v15
	v_pk_mul_f32 v[12:13], v[36:37], v[178:179]
	s_nop 0
	v_sub_f32_e32 v15, v12, v13
	v_or_b32_e32 v12, 48, v43
	v_sub_u32_e32 v12, v12, v41
	v_cvt_f32_ubyte0_e32 v179, v12
	v_mov_b32_e32 v36, v8
	v_add_u32_e32 v8, 47, v50
	v_pk_mul_f32 v[12:13], v[36:37], v[178:179]
	v_cvt_f32_u32_e32 v179, v8
	v_mov_b32_e32 v36, v9
	v_sub_f32_e32 v12, v12, v13
	v_max3_f32 v34, v34, v14, v15
	v_pk_mul_f32 v[8:9], v[36:37], v[178:179]
	v_mov_b32_e32 v36, v10
	v_sub_f32_e32 v13, v8, v9
	v_add_u32_e32 v8, 46, v50
	v_cvt_f32_u32_e32 v179, v8
	v_max3_f32 v34, v34, v12, v13
	v_pk_mul_f32 v[8:9], v[36:37], v[178:179]
	s_nop 0
	v_sub_f32_e32 v10, v8, v9
	v_add_u32_e32 v8, 45, v50
	v_cvt_f32_u32_e32 v179, v8
	v_mov_b32_e32 v36, v11
	v_pk_mul_f32 v[8:9], v[36:37], v[178:179]
	s_nop 0
	v_sub_f32_e32 v11, v8, v9
	v_or_b32_e32 v8, 32, v43
	v_sub_u32_e32 v8, v8, v41
	v_cvt_f32_ubyte0_e32 v179, v8
	v_mov_b32_e32 v36, v4
	v_add_u32_e32 v4, 31, v50
	v_pk_mul_f32 v[8:9], v[36:37], v[178:179]
	v_cvt_f32_u32_e32 v179, v4
	v_mov_b32_e32 v36, v5
	v_sub_f32_e32 v8, v8, v9
	v_max3_f32 v34, v34, v10, v11
	v_pk_mul_f32 v[4:5], v[36:37], v[178:179]
	v_mov_b32_e32 v36, v6
	v_sub_f32_e32 v9, v4, v5
	v_add_u32_e32 v4, 30, v50
	v_cvt_f32_u32_e32 v179, v4
	v_max3_f32 v34, v34, v8, v9
	v_pk_mul_f32 v[4:5], v[36:37], v[178:179]
	s_nop 0
	v_sub_f32_e32 v6, v4, v5
	v_add_u32_e32 v4, 29, v50
	v_cvt_f32_u32_e32 v179, v4
	v_mov_b32_e32 v36, v7
	v_pk_mul_f32 v[4:5], v[36:37], v[178:179]
	s_nop 0
	v_sub_f32_e32 v7, v4, v5
	v_or_b32_e32 v4, 16, v43
	v_sub_u32_e32 v4, v4, v41
	v_cvt_f32_ubyte0_e32 v179, v4
	v_mov_b32_e32 v36, v0
	v_add_u32_e32 v0, 15, v50
	v_pk_mul_f32 v[4:5], v[36:37], v[178:179]
	v_cvt_f32_u32_e32 v179, v0
	v_mov_b32_e32 v36, v1
	v_max3_f32 v34, v34, v6, v7
	v_sub_f32_e32 v5, v4, v5
	v_pk_mul_f32 v[0:1], v[36:37], v[178:179]
	v_and_b32_e32 v4, 64, v202
	v_sub_f32_e32 v0, v0, v1
	v_max3_f32 v1, v34, v5, v0
	v_max3_f32 v1, v1, v2, v3
	v_max3_f32 v1, v1, v28, v29
	v_max3_f32 v1, v1, v30, v31
	v_or_b32_e32 v4, v4, v41
	s_nop 0
	v_mov_b32_e32 v58, v1
	v_mov_b32_e32 v59, v1
	s_nop 1
	v_permlane16_swap_b32_e32 v58, v59
	s_nop 0
	v_max_f32_e32 v1, v58, v59
	s_nop 0
	v_mov_b32_e32 v58, v1
	v_mov_b32_e32 v59, v1
	s_nop 1
	v_permlane32_swap_b32_e32 v58, v59
	s_nop 0
	v_max_f32_e32 v1, v58, v59
	v_sub_f32_e32 v36, v44, v1
	v_mul_f32_e32 v36, 0x3fb8aa3b, v36
	v_sub_f32_e32 v43, v45, v1
	v_exp_f32_e32 v36, v36
	v_mul_f32_e32 v43, 0x3fb8aa3b, v43
	v_sub_f32_e32 v44, v46, v1
	v_exp_f32_e32 v43, v43
	v_mul_f32_e32 v44, 0x3fb8aa3b, v44
	v_sub_f32_e32 v45, v49, v1
	v_exp_f32_e32 v44, v44
	v_mul_f32_e32 v45, 0x3fb8aa3b, v45
	v_sub_f32_e32 v24, v24, v1
	v_exp_f32_e32 v45, v45
	v_mul_f32_e32 v24, 0x3fb8aa3b, v24
; DEV f32x4 mfma16(bf16x4 a, bf16x4 b, f32x4 c) { return __builtin_amdgcn_mfma_f32_16x16x16bf16_1k(a, b, c, 0, 0, 0); }
; DEV void attn_sample_item(const Params& p, int l, int item, unsigned char* smem) {
;     ...
;     float sum = 0.f;
; #pragma unroll
;     for (int t = 0; t < 9; ++t)
; #pragma unroll
;       for (int j = 0; j < 4; ++j) { const float e = __expf(s[t][j] - mx); s[t][j] = e; sum += e; }
;     sum += __shfl_xor(sum, 16); sum += __shfl_xor(sum, 32);
;     const float denom = sum + __expf(sink - mx);
;     f32x4 o = (f32x4){0.f, 0.f, 0.f, 0.f};
; #pragma unroll
;     for (int t = 0; t < 9; ++t) {
;       const bf16x4 pf = pack4(s[t][0], s[t][1], s[t][2], s[t][3]);
;       const bf16x4 vf = *(const bf16x4*)(Vt + (dt * 16 + fr) * 152 + t * 16 + fq * 4);
;       o = mfma16(pf, vf, o);
;     }
	v_sub_f32_e32 v25, v25, v1
	v_add_f32_e32 v37, 0, v36
	v_exp_f32_e32 v24, v24
	v_mul_f32_e32 v25, 0x3fb8aa3b, v25
	v_sub_f32_e32 v26, v26, v1
	v_add_f32_e32 v37, v43, v37
	v_exp_f32_e32 v25, v25
	v_mul_f32_e32 v26, 0x3fb8aa3b, v26
	v_sub_f32_e32 v27, v27, v1
	v_add_f32_e32 v37, v44, v37
	v_exp_f32_e32 v26, v26
	v_mul_f32_e32 v27, 0x3fb8aa3b, v27
	v_sub_f32_e32 v20, v20, v1
	v_add_f32_e32 v37, v45, v37
	v_exp_f32_e32 v27, v27
	v_mul_f32_e32 v20, 0x3fb8aa3b, v20
	v_sub_f32_e32 v21, v21, v1
	v_add_f32_e32 v37, v24, v37
	v_exp_f32_e32 v20, v20
	v_mul_f32_e32 v21, 0x3fb8aa3b, v21
	v_sub_f32_e32 v32, v32, v1
	v_add_f32_e32 v37, v25, v37
	v_exp_f32_e32 v21, v21
	v_mul_f32_e32 v32, 0x3fb8aa3b, v32
	v_sub_f32_e32 v33, v33, v1
	v_add_f32_e32 v37, v26, v37
	v_exp_f32_e32 v32, v32
	v_mul_f32_e32 v33, 0x3fb8aa3b, v33
	v_sub_f32_e32 v22, v22, v1
	v_add_f32_e32 v37, v27, v37
	v_exp_f32_e32 v33, v33
	v_mul_f32_e32 v22, 0x3fb8aa3b, v22
	v_sub_f32_e32 v23, v23, v1
	v_add_f32_e32 v37, v20, v37
	v_exp_f32_e32 v22, v22
	v_mul_f32_e32 v23, 0x3fb8aa3b, v23
	v_sub_f32_e32 v18, v18, v1
	v_add_f32_e32 v37, v21, v37
	v_exp_f32_e32 v23, v23
	v_mul_f32_e32 v18, 0x3fb8aa3b, v18
	v_sub_f32_e32 v19, v19, v1
	v_add_f32_e32 v37, v32, v37
	v_exp_f32_e32 v18, v18
	v_mul_f32_e32 v19, 0x3fb8aa3b, v19
	v_sub_f32_e32 v16, v16, v1
	v_add_f32_e32 v37, v33, v37
	v_exp_f32_e32 v19, v19
	v_mul_f32_e32 v16, 0x3fb8aa3b, v16
	v_sub_f32_e32 v17, v17, v1
	v_add_f32_e32 v37, v22, v37
	v_exp_f32_e32 v16, v16
	v_mul_f32_e32 v17, 0x3fb8aa3b, v17
	v_sub_f32_e32 v14, v14, v1
	v_add_f32_e32 v37, v23, v37
	v_exp_f32_e32 v17, v17
	v_mul_f32_e32 v14, 0x3fb8aa3b, v14
	v_sub_f32_e32 v15, v15, v1
	v_add_f32_e32 v37, v18, v37
	v_exp_f32_e32 v14, v14
	v_mul_f32_e32 v15, 0x3fb8aa3b, v15
	v_sub_f32_e32 v12, v12, v1
	v_add_f32_e32 v37, v19, v37
	v_exp_f32_e32 v15, v15
	v_mul_f32_e32 v12, 0x3fb8aa3b, v12
	v_add_f32_e32 v37, v16, v37
	v_exp_f32_e32 v46, v12
	v_add_f32_e32 v37, v17, v37
	v_add_f32_e32 v37, v14, v37
	v_sub_f32_e32 v13, v13, v1
	v_add_f32_e32 v37, v15, v37
	v_mul_f32_e32 v13, 0x3fb8aa3b, v13
	v_sub_f32_e32 v10, v10, v1
	v_add_f32_e32 v12, v46, v37
	v_exp_f32_e32 v37, v13
	v_mul_f32_e32 v10, 0x3fb8aa3b, v10
	v_sub_f32_e32 v11, v11, v1
	v_exp_f32_e32 v49, v10
	v_mul_f32_e32 v11, 0x3fb8aa3b, v11
	v_sub_f32_e32 v8, v8, v1
	v_exp_f32_e32 v11, v11
	v_mul_f32_e32 v8, 0x3fb8aa3b, v8
	v_sub_f32_e32 v9, v9, v1
	v_sub_f32_e32 v2, v2, v1
	v_exp_f32_e32 v50, v8
	v_mul_f32_e32 v9, 0x3fb8aa3b, v9
	v_sub_f32_e32 v6, v6, v1
	v_mul_f32_e32 v2, 0x3fb8aa3b, v2
	v_add_f32_e32 v12, v37, v12
	v_exp_f32_e32 v51, v9
	v_mul_f32_e32 v6, 0x3fb8aa3b, v6
	v_sub_f32_e32 v7, v7, v1
	v_exp_f32_e32 v55, v2
	v_sub_f32_e32 v2, v3, v1
	v_add_f32_e32 v10, v49, v12
	v_exp_f32_e32 v52, v6
	v_mul_f32_e32 v7, 0x3fb8aa3b, v7
	v_sub_f32_e32 v5, v5, v1
	v_mul_f32_e32 v2, 0x3fb8aa3b, v2
	v_add_f32_e32 v10, v11, v10
	v_exp_f32_e32 v53, v7
	v_mul_f32_e32 v5, 0x3fb8aa3b, v5
	v_sub_f32_e32 v0, v0, v1
	v_exp_f32_e32 v56, v2
	v_sub_f32_e32 v2, v28, v1
	v_add_f32_e32 v8, v50, v10
	v_exp_f32_e32 v5, v5
	v_mul_f32_e32 v0, 0x3fb8aa3b, v0
	v_mul_f32_e32 v2, 0x3fb8aa3b, v2
	v_add_f32_e32 v8, v51, v8
	v_exp_f32_e32 v54, v0
	v_exp_f32_e32 v28, v2
	v_sub_f32_e32 v2, v29, v1
	v_add_f32_e32 v6, v52, v8
	v_mul_f32_e32 v2, 0x3fb8aa3b, v2
	v_add_f32_e32 v6, v53, v6
	v_exp_f32_e32 v29, v2
	v_sub_f32_e32 v2, v30, v1
	v_add_f32_e32 v6, v5, v6
	v_mul_f32_e32 v2, 0x3fb8aa3b, v2
	v_add_f32_e32 v0, v54, v6
	v_exp_f32_e32 v30, v2
	v_sub_f32_e32 v2, v31, v1
	v_add_f32_e32 v0, v55, v0
	v_mul_f32_e32 v2, 0x3fb8aa3b, v2
	v_add_f32_e32 v0, v56, v0
	v_exp_f32_e32 v31, v2
	v_add_f32_e32 v0, v28, v0
	v_add_f32_e32 v0, v29, v0
	v_add_f32_e32 v0, v30, v0
	v_add_f32_e32 v0, v31, v0
	v_mov_b32_e32 v58, v0
	v_mov_b32_e32 v59, v0
	v_cvt_pk_bf16_f32 v6, v36, v43
	v_cvt_pk_bf16_f32 v7, v44, v45
	v_permlane16_swap_b32_e32 v58, v59
	v_cvt_pk_bf16_f32 v12, v20, v21
	v_cvt_pk_bf16_f32 v13, v32, v33
	v_add_f32_e32 v34, v58, v59
	v_sub_f32_e32 v0, v42, v1
	v_mul_f32_e32 v0, 0x3fb8aa3b, v0
	v_exp_f32_e32 v42, v0
	v_bfi_b32 v0, -16, v48, v47
	v_mul_lo_u32 v0, v0, s0
	v_lshlrev_b32_e32 v1, 3, v40
	v_add3_u32 v40, 0, v0, v1
	v_add_u32_e32 v36, 0x5000, v40
	ds_read2_b64 v[64:67], v36 offset0:32 offset1:36
	ds_read2_b64 v[68:71], v36 offset0:40 offset1:44
	ds_read2_b64 v[72:75], v36 offset0:48 offset1:52
	ds_read2_b64 v[76:79], v36 offset0:56 offset1:60
	ds_read_b64 v[80:81], v40 offset:20992
	v_mov_b32_e32 v58, v34
	v_mov_b32_e32 v35, v34
	s_waitcnt lgkmcnt(4)
; DEV bf16_t f2bf(float f) { return (bf16_t)(cvt_pk_bf16(f, 0.f) & 0xffffu); }
; DEV f32x4 mfma16(bf16x4 a, bf16x4 b, f32x4 c) { return __builtin_amdgcn_mfma_f32_16x16x16bf16_1k(a, b, c, 0, 0, 0); }
; DEV void attn_sample_item(const Params& p, int l, int item, unsigned char* smem) {
;     ...
;     sum += __shfl_xor(sum, 16); sum += __shfl_xor(sum, 32);
;     const float denom = sum + __expf(sink - mx);
;     f32x4 o = (f32x4){0.f, 0.f, 0.f, 0.f};
; #pragma unroll
;     for (int t = 0; t < 9; ++t) {
;       const bf16x4 pf = pack4(s[t][0], s[t][1], s[t][2], s[t][3]);
;       const bf16x4 vf = *(const bf16x4*)(Vt + (dt * 16 + fr) * 152 + t * 16 + fq * 4);
;       o = mfma16(pf, vf, o);
;     }
; #pragma unroll
;     for (int j = 0; j < 4; ++j) {
;       const int ro = qt * 16 + fq * 4 + j;
;       const float inv = 1.0f / __shfl(denom, fq * 4 + j);
;       Z[(rowbase + (ro & 7)) * NIN + AQ + (kvh * 4 + (ro >> 3)) * 64 + dt * 16 + fr] = f2bf(o[j] * inv);
;     }
	v_mfma_f32_16x16x16_bf16 v[6:9], v[6:7], v[64:65], 0
	v_cvt_pk_bf16_f32 v0, v24, v25
	v_cvt_pk_bf16_f32 v1, v26, v27
	v_permlane32_swap_b32_e32 v58, v35
	v_and_b32_e32 v10, -16, v48
	v_mfma_f32_16x16x16_bf16 v[0:3], v[0:1], v[66:67], v[6:9]
	s_waitcnt lgkmcnt(3)
	v_mfma_f32_16x16x16_bf16 v[0:3], v[12:13], v[68:69], v[0:3]
	s_nop 0
	v_cvt_pk_bf16_f32 v6, v22, v23
	v_cvt_pk_bf16_f32 v7, v18, v19
	v_cvt_pk_bf16_f32 v12, v16, v17
	v_cvt_pk_bf16_f32 v13, v14, v15
	v_mfma_f32_16x16x16_bf16 v[0:3], v[6:7], v[70:71], v[0:3]
	s_waitcnt lgkmcnt(2)
	v_mfma_f32_16x16x16_bf16 v[0:3], v[12:13], v[72:73], v[0:3]
	v_cvt_pk_bf16_f32 v6, v46, v37
	v_cvt_pk_bf16_f32 v7, v49, v11
	v_cvt_pk_bf16_f32 v12, v50, v51
	v_cvt_pk_bf16_f32 v13, v52, v53
	v_mfma_f32_16x16x16_bf16 v[0:3], v[6:7], v[74:75], v[0:3]
	v_ashrrev_i32_e32 v11, 31, v10
	s_waitcnt lgkmcnt(1)
	v_mfma_f32_16x16x16_bf16 v[0:3], v[12:13], v[76:77], v[0:3]
	v_cvt_pk_bf16_f32 v6, v5, v54
	v_cvt_pk_bf16_f32 v7, v55, v56
	v_add_f32_e32 v5, v58, v35
	s_nop 0
	v_mfma_f32_16x16x16_bf16 v[0:3], v[6:7], v[78:79], v[0:3]
	v_cvt_pk_bf16_f32 v6, v28, v29
	v_cvt_pk_bf16_f32 v7, v30, v31
	s_waitcnt lgkmcnt(0)
	s_nop 0
	v_mfma_f32_16x16x16_bf16 v[0:3], v[6:7], v[80:81], v[0:3]
	v_add_f32_e32 v8, v42, v5
	v_lshlrev_b32_e32 v9, 2, v4
	v_rcp_f32_e32 v58, v8
	v_lshl_add_u64 v[6:7], v[10:11], 1, s[30:31]
	v_fma_f32 v59, -v8, v58, 1.0
	v_fmac_f32_e32 v58, v59, v58
	v_or_b32_e32 v5, v39, v41
	v_lshrrev_b32_e32 v5, 3, v5
	ds_bpermute_b32 v60, v9, v58
	ds_bpermute_b32 v61, v9, v58 offset:4
	ds_bpermute_b32 v62, v9, v58 offset:8
	ds_bpermute_b32 v63, v9, v58 offset:12
	v_or_b32_e32 v5, s2, v5
	v_lshl_add_u64 v[6:7], v[6:7], 0, v[168:169]
	v_and_or_b32 v4, v41, 4, s6
	s_movk_i32 s0, 0x1b00
	v_mul_lo_u32 v4, v4, s0
	v_lshl_add_u32 v168, v5, 6, v4
	v_lshl_add_u64 v[4:5], v[168:169], 1, v[6:7]
	v_add_co_u32_e32 v6, vcc, 0x4000, v4
	s_nop 1
	v_addc_co_u32_e32 v7, vcc, 0, v5, vcc
	s_nop 1
	v_add_co_u32_e32 v10, vcc, 0x7000, v4
	s_nop 1
	v_addc_co_u32_e32 v11, vcc, 0, v5, vcc
	s_nop 1
	v_add_co_u32_e32 v12, vcc, 0xa000, v4
	s_nop 1
	v_addc_co_u32_e32 v13, vcc, 0, v5, vcc
	s_waitcnt lgkmcnt(0)
	v_mul_f32_e32 v0, v0, v60
	v_mul_f32_e32 v1, v1, v61
	v_mul_f32_e32 v2, v2, v62
	v_mul_f32_e32 v3, v3, v63
	v_cvt_pk_bf16_f32 v0, v0, s0
	v_cvt_pk_bf16_f32 v1, v1, s0
	v_cvt_pk_bf16_f32 v2, v2, s0
	v_cvt_pk_bf16_f32 v3, v3, s0
	global_store_short v[4:5], v0, off offset:3072
	global_store_short v[6:7], v1, off offset:512
	global_store_short v[10:11], v2, off offset:2048
	global_store_short v[12:13], v3, off offset:3584
	s_mov_b64 s[0:1], 0
	s_barrier
